# gu_bar3
# baseline (speedup 1.0000x reference)
; #define STAGE_A(P, br, kt) do { const char* _base = (const char*)(((kt) < G.ksplit ? G.A1 : A2m) + (long)(br) * G.lda + (long)(kt) * BK); \
;     __builtin_amdgcn_global_load_lds((const unsigned*)(_base + aoff0), (unsigned*)((char*)(P) + sb0), 16, 0, 0); \
;     __builtin_amdgcn_global_load_lds((const unsigned*)(_base + aoff1), (unsigned*)((char*)(P) + sb1), 16, 0, 0); } while (0)
; #define STAGE_B(P, br, kt) do { const char* _base = (const char*)(G.Bt + (long)(br) * G.ldb + (long)(kt) * BK); \
;     __builtin_amdgcn_global_load_lds((const unsigned*)(_base + boff0), (unsigned*)((char*)(P) + sb0), 16, 0, 0); \
;     __builtin_amdgcn_global_load_lds((const unsigned*)(_base + boff1), (unsigned*)((char*)(P) + sb1), 16, 0, 0); } while (0)
; #define WAIT_V(n) asm volatile("s_waitcnt vmcnt(" #n ")" ::: "memory")
; #define BAR __builtin_amdgcn_s_barrier()
;     ...
;   if (EPI == EPI_RESID || first) {
;     STAGE_B(SB(0, 0), bcol, 0); STAGE_A(SA(0, 0), brow, 0);
;     STAGE_B(SB(0, 1), bcol + HALF, 0); STAGE_A(SA(0, 1), brow + HALF, 0);
;   }
;   if (wr == 1) BAR;
;   WAIT_V(0); BAR;
.LBB0_2563:
	s_barrier
	v_ashrrev_i32_e32 v151, 8, v144
	v_cmp_eq_u32_e32 vcc, 1, v151
	s_and_saveexec_b64 s[20:21], vcc
	s_cbranch_execz .LBB0_2565
	s_barrier

; #define STAGE_A(P, br, kt) do { const char* _base = (const char*)(((kt) < G.ksplit ? G.A1 : A2m) + (long)(br) * G.lda + (long)(kt) * BK); \
;     __builtin_amdgcn_global_load_lds((const unsigned*)(_base + aoff0), (unsigned*)((char*)(P) + sb0), 16, 0, 0); \
;     __builtin_amdgcn_global_load_lds((const unsigned*)(_base + aoff1), (unsigned*)((char*)(P) + sb1), 16, 0, 0); } while (0)
; #define STAGE_B(P, br, kt) do { const char* _base = (const char*)(G.Bt + (long)(br) * G.ldb + (long)(kt) * BK); \
;     __builtin_amdgcn_global_load_lds((const unsigned*)(_base + boff0), (unsigned*)((char*)(P) + sb0), 16, 0, 0); \
;     __builtin_amdgcn_global_load_lds((const unsigned*)(_base + boff1), (unsigned*)((char*)(P) + sb1), 16, 0, 0); } while (0)
; #define LDA(dst, b, h) for (int m = 0; m < 4; ++m) for (int k = 0; k < 2; ++k) \
;     dst[m][k] = *reinterpret_cast<const bf16x8*>(a_rd + ((b) * 2 + (h)) * (HT * 2) + m * 2048 + k * 1024)
; #define MMA(ai, bj, At_, Bt_) do { __builtin_amdgcn_s_setprio(1); \
;     for (int m = 0; m < 4; ++m) for (int n = 0; n < 2; ++n) for (int k = 0; k < 2; ++k) \
;       acc[ai][bj][m][n] = __builtin_amdgcn_mfma_f32_16x16x32_bf16(Bt_[n][k], At_[m][k], acc[ai][bj][m][n], 0, 0, 0); \
;     __builtin_amdgcn_s_setprio(0); } while (0)
; #define WAIT_L(n) asm volatile("s_waitcnt lgkmcnt(" #n ")" ::: "memory")
; #define BAR __builtin_amdgcn_s_barrier()
; __device__ __forceinline__ KPtr kargs() { KPtr p = (KPtr)__builtin_amdgcn_kernarg_segment_ptr(); asm volatile("" : "+s"(p)); return p; }
;     ...
;     LDA(At, 1, 1); BAR; WAIT_L(0); MMA(1, 0, At, B0); MMA(1, 1, At, B1); BAR; }
;   if (wr == 0) BAR;
;   if (EPI != EPI_RESID && has_next) {
;     STAGE_B(SB(0, 0), nbcol, 0); STAGE_A(SA(0, 0), nbrow, 0);
;     STAGE_B(SB(0, 1), nbcol + HALF, 0); STAGE_A(SA(0, 1), nbrow + HALF, 0);
;   }
; __device__ __forceinline__ void xcd_barrier() {
;   asm volatile("s_waitcnt vmcnt(0)" ::: "memory");
;   __syncthreads();
;   if (otid() == 0) {
;     unsigned* bar = (unsigned*)(kargs()->ws + OFF_MISC + 65536);
;     const uint4 t_ = g_xb_sh; struct { unsigned x, nloc, nx; } b = {t_.x, t_.y, t_.z};
;     __builtin_amdgcn_s_waitcnt(0);
;     const unsigned old = xb_add(&bar[XB_XSUB(b.x)], 1u);
;     const unsigned gen = old / b.nloc;
;     if (old + 1u == (gen + 1u) * b.nloc) {
.Lmy_gu_t6skip:
	v_mfma_f32_16x16x32_bf16 v[0:3], v[214:217], v[148:151], v[0:3]
	v_mfma_f32_16x16x32_bf16 v[4:7], v[230:233], v[148:151], v[4:7]
	s_setprio 0
	s_andn2_b64 vcc, exec, s[16:17]
	v_mov_b32_e32 v249, v245
	s_cbranch_vccnz .LBB0_2558
	s_mul_i32 s16, s27, 0x840
	s_ashr_i32 s17, s16, 31
	s_lshl_b64 s[16:17], s[16:17], 1
	s_add_u32 s16, s8, s16
	s_addc_u32 s17, s9, s17
	v_readfirstlane_b32 s18, v159
	v_lshl_add_u64 v[140:141], s[16:17], 0, v[180:181]
	s_mov_b32 m0, s18
	s_mul_i32 s18, s26, 0x1080
	global_load_lds_dwordx4 v[140:141], off
	v_lshl_add_u64 v[140:141], s[16:17], 0, v[128:129]
	v_readfirstlane_b32 s16, v160
	s_mov_b32 m0, s16
	s_mul_hi_i32 s17, s26, 0x1080
	s_add_u32 s16, s23, s18
	s_addc_u32 s17, s24, s17
	v_readfirstlane_b32 s19, v147
	global_load_lds_dwordx4 v[140:141], off
	v_lshl_add_u64 v[140:141], s[16:17], 0, v[180:181]
	s_mov_b32 m0, s19
	v_readfirstlane_b32 s19, v145
	global_load_lds_dwordx4 v[140:141], off
	v_lshl_add_u64 v[140:141], s[16:17], 0, v[128:129]
	v_readfirstlane_b32 s16, v146
	s_mov_b32 m0, s16
	s_or_b32 s16, s27, 0x80
	s_mul_hi_i32 s17, s16, 0x1080
	s_mulk_i32 s16, 0x1080
	s_add_u32 s16, s8, s16
	s_addc_u32 s17, s9, s17
	global_load_lds_dwordx4 v[140:141], off
	v_lshl_add_u64 v[140:141], s[16:17], 0, v[180:181]
	s_mov_b32 m0, s19
	s_add_i32 s18, s18, 0x84000
	global_load_lds_dwordx4 v[140:141], off
	v_lshl_add_u64 v[140:141], s[16:17], 0, v[128:129]
	v_readfirstlane_b32 s16, v161
	s_mov_b32 m0, s16
	s_add_i32 s16, s26, 0x80
	s_mul_hi_i32 s17, s16, 0x1080
	s_add_u32 s16, s23, s18
	s_addc_u32 s17, s24, s17
	v_readfirstlane_b32 s18, v143
	global_load_lds_dwordx4 v[140:141], off
	v_lshl_add_u64 v[140:141], s[16:17], 0, v[180:181]
	s_mov_b32 m0, s18
	v_lshl_add_u64 v[128:129], s[16:17], 0, v[128:129]
	v_readfirstlane_b32 s16, v142
	global_load_lds_dwordx4 v[140:141], off
	s_mov_b32 m0, s16
	s_nop 0
	global_load_lds_dwordx4 v[128:129], off
	s_branch .LBB0_2558
.Lmy_gu_exitbar:
	s_barrier
.LBB0_2571:
	v_readfirstlane_b32 s8, v224
	s_waitcnt vmcnt(0)
	s_andn2_b32 s8, s8, 63
	s_waitcnt lgkmcnt(0)
	v_add_u32_e32 v0, s8, v225
	s_barrier
	s_nop 0
	v_cmp_eq_u32_e32 vcc, 0, v0
	s_and_saveexec_b64 s[8:9], vcc
	s_cbranch_execz .LBB0_2608
	s_mov_b64 s[10:11], s[0:1]
	ds_read_b96 v[0:2], v181
	s_load_dwordx2 s[10:11], s[10:11], 0xc8
	s_mov_b64 s[12:13], exec
	s_waitcnt vmcnt(0) expcnt(0) lgkmcnt(0)
	v_readfirstlane_b32 s14, v0
	v_mbcnt_lo_u32_b32 v0, s12, 0
	s_add_u32 s38, s10, 0x3f010000
	v_mbcnt_hi_u32_b32 v0, s13, v0
	s_addc_u32 s34, s11, 0
	s_lshl_b32 s35, s14, 6
	v_cmp_eq_u32_e32 vcc, 0, v0
	s_and_saveexec_b64 s[14:15], vcc
	s_cbranch_execz .LBB0_2574
	v_readlane_b32 s16, v253, 15
	v_readlane_b32 s17, v253, 16
	s_add_i32 s16, s35, 0x500
	s_mov_b32 s37, s17
	s_lshl_b64 s[16:17], s[16:17], 2
	v_readlane_b32 s18, v253, 17
	v_readlane_b32 s19, v253, 18
	v_readlane_b32 s20, v253, 19
	v_readlane_b32 s21, v253, 20
	v_readlane_b32 s22, v253, 21
	v_readlane_b32 s23, v253, 22
	v_readlane_b32 s24, v253, 23
	v_readlane_b32 s25, v253, 24
	v_readlane_b32 s26, v253, 25
	v_readlane_b32 s27, v253, 26
	v_readlane_b32 s28, v253, 27
	v_readlane_b32 s29, v253, 28
	v_readlane_b32 s30, v253, 29
	v_readlane_b32 s31, v253, 30
	v_writelane_b32 v253, s36, 15
	s_add_u32 s16, s38, s16
	s_addc_u32 s17, s34, s17
	s_bcnt1_i32_b64 s12, s[12:13]
	v_mov_b32_e32 v3, s12
	global_atomic_add v3, v181, v3, s[16:17] sc0
	v_writelane_b32 v253, s37, 16
	v_writelane_b32 v253, s38, 17
	v_writelane_b32 v253, s39, 18
	v_writelane_b32 v253, s40, 19
	v_writelane_b32 v253, s41, 20
	v_writelane_b32 v253, s42, 21
	v_writelane_b32 v253, s43, 22
	v_writelane_b32 v253, s44, 23
	v_writelane_b32 v253, s45, 24
	v_writelane_b32 v253, s46, 25
	v_writelane_b32 v253, s47, 26
	v_writelane_b32 v253, s48, 27
	v_writelane_b32 v253, s49, 28
	v_writelane_b32 v253, s50, 29
	v_writelane_b32 v253, s51, 30
